# SwiGLU epilogues (P2, P11): scalar mul/add pairs fused into v_pk_mul_f32 / v_pk_add_f32 (same f32 math, fewer VALU issues)
# speedup vs baseline: 1.0022x; 1.0022x over previous
.Lkx_1:
	v_mov_b32_e32 v244, 0xbfb8aa3b
	s_mov_b32 s99, 1

.LBB0_438:
	v_mul_f32_e32 v165, 0xbfb8aa3b, v124
	v_exp_f32_e32 v166, v165
	v_mul_f32_e32 v165, 0xbfb8aa3b, v125
	v_exp_f32_e32 v167, v165
	s_ashr_i32 s91, s90, 31
	v_pk_add_f32 v[166:167], v[166:167], 1.0 op_sel_hi:[1,0]
	v_rcp_f32_e32 v166, v166
	v_rcp_f32_e32 v167, v167
	s_lshl_b64 s[52:53], s[90:91], 8
	v_mov_b32_e32 v168, v145
	v_mov_b32_e32 v164, v144
	v_pk_mul_f32 v[124:125], v[124:125], v[166:167]
	v_pk_mul_f32 v[166:167], v[126:127], v[244:245] op_sel_hi:[1,0]
	v_exp_f32_e32 v166, v166
	v_exp_f32_e32 v167, v167
	v_pk_mul_f32 v[120:121], v[120:121], v[124:125]
	s_add_u32 s52, s52, s31
	v_add_f32_e32 v124, 1.0, v166
	v_add_f32_e32 v125, 1.0, v167
	v_pk_mul_f32 v[166:167], v[116:117], v[244:245] op_sel_hi:[1,0]
	v_rcp_f32_e32 v124, v124
	v_rcp_f32_e32 v125, v125
	v_exp_f32_e32 v166, v166
	v_exp_f32_e32 v167, v167
	v_pk_mul_f32 v[124:125], v[126:127], v[124:125]
	v_add_f32_e32 v126, 1.0, v166
	v_add_f32_e32 v127, 1.0, v167
	v_pk_mul_f32 v[166:167], v[118:119], v[244:245] op_sel_hi:[1,0]
	v_exp_f32_e32 v166, v166
	v_exp_f32_e32 v167, v167
	v_rcp_f32_e32 v126, v126
	v_rcp_f32_e32 v127, v127
	v_pk_add_f32 v[166:167], v[166:167], 1.0 op_sel_hi:[1,0]
	v_rcp_f32_e32 v166, v166
	v_rcp_f32_e32 v167, v167
	v_pk_mul_f32 v[116:117], v[116:117], v[126:127]
	v_ashrrev_i32_e32 v165, 31, v164
	v_pk_mul_f32 v[112:113], v[112:113], v[116:117]
	v_pk_mul_f32 v[116:117], v[118:119], v[166:167]
	s_addc_u32 s53, s53, s34
	v_pk_mul_f32 v[122:123], v[122:123], v[124:125]
	v_pk_mul_f32 v[118:119], v[114:115], v[116:117]
	v_lshl_add_u64 v[124:125], s[52:53], 0, v[164:165]
	v_cvt_pk_bf16_f32 v116, v112, v113
	v_mov_b64_e32 v[112:113], s[64:65]
	v_cvt_pk_bf16_f32 v117, v118, v119
	v_mad_u64_u32 v[112:113], s[52:53], v124, s73, v[112:113]
	v_pk_mul_f32 v[118:119], v[108:109], v[244:245] op_sel_hi:[1,0]
	s_lshl_b32 s52, s81, 7
	v_exp_f32_e32 v118, v118
	v_exp_f32_e32 v119, v119
	v_mad_i32_i24 v113, v125, s73, v113
	s_ashr_i32 s53, s52, 31
	v_lshlrev_b32_e32 v168, 3, v168
	v_lshl_add_u64 v[112:113], s[52:53], 1, v[112:113]
	v_ashrrev_i32_e32 v169, 31, v168
	v_lshl_add_u64 v[112:113], v[112:113], 0, s[70:71]
	v_cvt_pk_bf16_f32 v114, v120, v121
	v_cvt_pk_bf16_f32 v115, v122, v123
	v_pk_add_f32 v[118:119], v[118:119], 1.0 op_sel_hi:[1,0]
	v_lshl_add_u64 v[112:113], v[168:169], 1, v[112:113]
	v_rcp_f32_e32 v118, v118
	v_rcp_f32_e32 v119, v119
	global_store_dwordx4 v[112:113], v[114:117], off
	s_mov_b32 s52, 0x16000
	v_pk_mul_f32 v[108:109], v[108:109], v[118:119]
	v_pk_mul_f32 v[114:115], v[110:111], v[244:245] op_sel_hi:[1,0]
	v_exp_f32_e32 v114, v114
	v_exp_f32_e32 v115, v115
	v_pk_mul_f32 v[104:105], v[104:105], v[108:109]
	v_add_f32_e32 v108, 1.0, v114
	v_add_f32_e32 v109, 1.0, v115
	v_pk_mul_f32 v[114:115], v[100:101], v[244:245] op_sel_hi:[1,0]
	v_rcp_f32_e32 v108, v108
	v_rcp_f32_e32 v109, v109
	v_exp_f32_e32 v114, v114
	v_exp_f32_e32 v115, v115
	v_pk_mul_f32 v[108:109], v[110:111], v[108:109]
	v_add_f32_e32 v110, 1.0, v114
	v_add_f32_e32 v111, 1.0, v115
	v_pk_mul_f32 v[114:115], v[102:103], v[244:245] op_sel_hi:[1,0]
	v_exp_f32_e32 v114, v114
	v_exp_f32_e32 v115, v115
	v_rcp_f32_e32 v110, v110
	v_rcp_f32_e32 v111, v111
	v_pk_add_f32 v[114:115], v[114:115], 1.0 op_sel_hi:[1,0]
	v_rcp_f32_e32 v114, v114
	v_rcp_f32_e32 v115, v115
	v_pk_mul_f32 v[100:101], v[100:101], v[110:111]
	v_pk_mul_f32 v[106:107], v[106:107], v[108:109]
	v_pk_mul_f32 v[100:101], v[96:97], v[100:101]
	v_pk_mul_f32 v[96:97], v[102:103], v[114:115]
	s_nop 0
	v_pk_mul_f32 v[102:103], v[98:99], v[96:97]
	v_mul_f32_e32 v99, 0xbfb8aa3b, v92
	v_cvt_pk_bf16_f32 v98, v100, v101
	v_exp_f32_e32 v100, v99
	v_mul_f32_e32 v99, 0xbfb8aa3b, v93
	v_exp_f32_e32 v101, v99
	v_cvt_pk_bf16_f32 v99, v102, v103
	v_add_co_u32_e32 v102, vcc, s52, v112
	v_cvt_pk_bf16_f32 v96, v104, v105
	v_cvt_pk_bf16_f32 v97, v106, v107
	v_pk_add_f32 v[100:101], v[100:101], 1.0 op_sel_hi:[1,0]
	v_addc_co_u32_e32 v103, vcc, 0, v113, vcc
	v_rcp_f32_e32 v100, v100
	v_rcp_f32_e32 v101, v101
	global_store_dwordx4 v[102:103], v[96:99], off
	s_mov_b32 s52, 0x2c000
	v_pk_mul_f32 v[92:93], v[92:93], v[100:101]
	v_pk_mul_f32 v[96:97], v[94:95], v[244:245] op_sel_hi:[1,0]
	v_exp_f32_e32 v96, v96
	v_exp_f32_e32 v97, v97
	v_pk_mul_f32 v[88:89], v[88:89], v[92:93]
	v_add_f32_e32 v92, 1.0, v96
	v_add_f32_e32 v93, 1.0, v97
	v_pk_mul_f32 v[96:97], v[84:85], v[244:245] op_sel_hi:[1,0]
	v_rcp_f32_e32 v92, v92
	v_rcp_f32_e32 v93, v93
	v_exp_f32_e32 v96, v96
	v_exp_f32_e32 v97, v97
	v_pk_mul_f32 v[92:93], v[94:95], v[92:93]
	v_add_f32_e32 v94, 1.0, v96
	v_add_f32_e32 v95, 1.0, v97
	v_pk_mul_f32 v[96:97], v[86:87], v[244:245] op_sel_hi:[1,0]
	v_exp_f32_e32 v96, v96
	v_exp_f32_e32 v97, v97
	v_rcp_f32_e32 v94, v94
	v_rcp_f32_e32 v95, v95
	v_pk_add_f32 v[96:97], v[96:97], 1.0 op_sel_hi:[1,0]
	v_rcp_f32_e32 v96, v96
	v_rcp_f32_e32 v97, v97
	v_pk_mul_f32 v[84:85], v[84:85], v[94:95]
	v_pk_mul_f32 v[90:91], v[90:91], v[92:93]
	v_pk_mul_f32 v[84:85], v[80:81], v[84:85]
	v_pk_mul_f32 v[80:81], v[86:87], v[96:97]
	s_nop 0
	v_pk_mul_f32 v[86:87], v[82:83], v[80:81]
	v_mul_f32_e32 v83, 0xbfb8aa3b, v76
	v_cvt_pk_bf16_f32 v82, v84, v85
	v_exp_f32_e32 v84, v83
	v_mul_f32_e32 v83, 0xbfb8aa3b, v77
	v_exp_f32_e32 v85, v83
	v_cvt_pk_bf16_f32 v83, v86, v87
	v_add_co_u32_e32 v86, vcc, s52, v112
	v_cvt_pk_bf16_f32 v80, v88, v89
	v_cvt_pk_bf16_f32 v81, v90, v91
	v_pk_add_f32 v[84:85], v[84:85], 1.0 op_sel_hi:[1,0]
	v_addc_co_u32_e32 v87, vcc, 0, v113, vcc
	v_rcp_f32_e32 v84, v84
	v_rcp_f32_e32 v85, v85
	global_store_dwordx4 v[86:87], v[80:83], off
	s_mov_b32 s52, 0x42000
	v_pk_mul_f32 v[76:77], v[76:77], v[84:85]
	v_pk_mul_f32 v[80:81], v[78:79], v[244:245] op_sel_hi:[1,0]
	v_exp_f32_e32 v80, v80
	v_exp_f32_e32 v81, v81
	v_pk_mul_f32 v[72:73], v[72:73], v[76:77]
	v_add_f32_e32 v76, 1.0, v80
	v_add_f32_e32 v77, 1.0, v81
	v_pk_mul_f32 v[80:81], v[68:69], v[244:245] op_sel_hi:[1,0]
	v_rcp_f32_e32 v76, v76
	v_rcp_f32_e32 v77, v77
	v_exp_f32_e32 v80, v80
	v_exp_f32_e32 v81, v81
	v_pk_mul_f32 v[76:77], v[78:79], v[76:77]
	v_add_f32_e32 v78, 1.0, v80
	v_add_f32_e32 v79, 1.0, v81
	v_pk_mul_f32 v[80:81], v[70:71], v[244:245] op_sel_hi:[1,0]
	v_exp_f32_e32 v80, v80
	v_exp_f32_e32 v81, v81
	v_rcp_f32_e32 v78, v78
	v_rcp_f32_e32 v79, v79
	v_pk_add_f32 v[80:81], v[80:81], 1.0 op_sel_hi:[1,0]
	v_rcp_f32_e32 v80, v80
	v_rcp_f32_e32 v81, v81
	v_pk_mul_f32 v[68:69], v[68:69], v[78:79]
	v_pk_mul_f32 v[74:75], v[74:75], v[76:77]
	v_pk_mul_f32 v[68:69], v[64:65], v[68:69]
	v_pk_mul_f32 v[64:65], v[70:71], v[80:81]
	s_nop 0
	v_pk_mul_f32 v[70:71], v[66:67], v[64:65]
	v_mul_f32_e32 v67, 0xbfb8aa3b, v60
	v_cvt_pk_bf16_f32 v66, v68, v69
	v_exp_f32_e32 v68, v67
	v_mul_f32_e32 v67, 0xbfb8aa3b, v61
	v_exp_f32_e32 v69, v67
	v_cvt_pk_bf16_f32 v67, v70, v71
	v_add_co_u32_e32 v70, vcc, s52, v112
	v_cvt_pk_bf16_f32 v64, v72, v73
	v_cvt_pk_bf16_f32 v65, v74, v75
	v_pk_add_f32 v[68:69], v[68:69], 1.0 op_sel_hi:[1,0]
	v_addc_co_u32_e32 v71, vcc, 0, v113, vcc
	v_rcp_f32_e32 v68, v68
	v_rcp_f32_e32 v69, v69
	global_store_dwordx4 v[70:71], v[64:67], off
	s_mov_b32 s52, 0xb0000
	v_pk_mul_f32 v[60:61], v[60:61], v[68:69]
	v_pk_mul_f32 v[64:65], v[62:63], v[244:245] op_sel_hi:[1,0]
	v_exp_f32_e32 v64, v64
	v_exp_f32_e32 v65, v65
	v_pk_mul_f32 v[56:57], v[56:57], v[60:61]
	v_add_f32_e32 v60, 1.0, v64
	v_add_f32_e32 v61, 1.0, v65
	v_pk_mul_f32 v[64:65], v[52:53], v[244:245] op_sel_hi:[1,0]
	v_rcp_f32_e32 v60, v60
	v_rcp_f32_e32 v61, v61
	v_exp_f32_e32 v64, v64
	v_exp_f32_e32 v65, v65
	v_pk_mul_f32 v[60:61], v[62:63], v[60:61]
	v_add_f32_e32 v62, 1.0, v64
	v_add_f32_e32 v63, 1.0, v65
	v_pk_mul_f32 v[64:65], v[54:55], v[244:245] op_sel_hi:[1,0]
	v_exp_f32_e32 v64, v64
	v_exp_f32_e32 v65, v65
	v_rcp_f32_e32 v62, v62
	v_rcp_f32_e32 v63, v63
	v_pk_add_f32 v[64:65], v[64:65], 1.0 op_sel_hi:[1,0]
	v_rcp_f32_e32 v64, v64
	v_rcp_f32_e32 v65, v65
	v_pk_mul_f32 v[52:53], v[52:53], v[62:63]
	v_pk_mul_f32 v[58:59], v[58:59], v[60:61]
	v_pk_mul_f32 v[52:53], v[48:49], v[52:53]
	v_pk_mul_f32 v[48:49], v[54:55], v[64:65]
	s_nop 0
	v_pk_mul_f32 v[54:55], v[50:51], v[48:49]
	v_mul_f32_e32 v51, 0xbfb8aa3b, v44
	v_cvt_pk_bf16_f32 v50, v52, v53
	v_exp_f32_e32 v52, v51
	v_mul_f32_e32 v51, 0xbfb8aa3b, v45
	v_exp_f32_e32 v53, v51
	v_cvt_pk_bf16_f32 v51, v54, v55
	v_add_co_u32_e32 v54, vcc, s52, v112
	v_cvt_pk_bf16_f32 v48, v56, v57
	v_cvt_pk_bf16_f32 v49, v58, v59
	v_pk_add_f32 v[52:53], v[52:53], 1.0 op_sel_hi:[1,0]
	v_addc_co_u32_e32 v55, vcc, 0, v113, vcc
	v_rcp_f32_e32 v52, v52
	v_rcp_f32_e32 v53, v53
	global_store_dwordx4 v[54:55], v[48:51], off
	s_mov_b32 s52, 0xc6000
	v_pk_mul_f32 v[44:45], v[44:45], v[52:53]
	v_pk_mul_f32 v[48:49], v[46:47], v[244:245] op_sel_hi:[1,0]
	v_exp_f32_e32 v48, v48
	v_exp_f32_e32 v49, v49
	v_pk_mul_f32 v[40:41], v[40:41], v[44:45]
	v_add_f32_e32 v44, 1.0, v48
	v_add_f32_e32 v45, 1.0, v49
	v_pk_mul_f32 v[48:49], v[36:37], v[244:245] op_sel_hi:[1,0]
	v_rcp_f32_e32 v44, v44
	v_rcp_f32_e32 v45, v45
	v_exp_f32_e32 v48, v48
	v_exp_f32_e32 v49, v49
	v_pk_mul_f32 v[44:45], v[46:47], v[44:45]
	v_add_f32_e32 v46, 1.0, v48
	v_add_f32_e32 v47, 1.0, v49
	v_pk_mul_f32 v[48:49], v[38:39], v[244:245] op_sel_hi:[1,0]
	v_exp_f32_e32 v48, v48
	v_exp_f32_e32 v49, v49
	v_rcp_f32_e32 v46, v46
	v_rcp_f32_e32 v47, v47
	v_pk_add_f32 v[48:49], v[48:49], 1.0 op_sel_hi:[1,0]
	v_rcp_f32_e32 v48, v48
	v_rcp_f32_e32 v49, v49
	v_pk_mul_f32 v[36:37], v[36:37], v[46:47]
	v_pk_mul_f32 v[42:43], v[42:43], v[44:45]
	v_pk_mul_f32 v[36:37], v[32:33], v[36:37]
	v_pk_mul_f32 v[32:33], v[38:39], v[48:49]
	s_nop 0
	v_pk_mul_f32 v[38:39], v[34:35], v[32:33]
	v_mul_f32_e32 v35, 0xbfb8aa3b, v28
	v_cvt_pk_bf16_f32 v34, v36, v37
	v_exp_f32_e32 v36, v35
	v_mul_f32_e32 v35, 0xbfb8aa3b, v29
	v_exp_f32_e32 v37, v35
	v_cvt_pk_bf16_f32 v35, v38, v39
	v_add_co_u32_e32 v38, vcc, s52, v112
	v_cvt_pk_bf16_f32 v32, v40, v41
	v_cvt_pk_bf16_f32 v33, v42, v43
	v_pk_add_f32 v[36:37], v[36:37], 1.0 op_sel_hi:[1,0]
	v_addc_co_u32_e32 v39, vcc, 0, v113, vcc
	v_rcp_f32_e32 v36, v36
	v_rcp_f32_e32 v37, v37
	global_store_dwordx4 v[38:39], v[32:35], off
	s_mov_b32 s52, 0xdc000
	v_pk_mul_f32 v[28:29], v[28:29], v[36:37]
	v_pk_mul_f32 v[32:33], v[30:31], v[244:245] op_sel_hi:[1,0]
	v_exp_f32_e32 v32, v32
	v_exp_f32_e32 v33, v33
	v_pk_mul_f32 v[24:25], v[24:25], v[28:29]
	v_add_f32_e32 v28, 1.0, v32
	v_add_f32_e32 v29, 1.0, v33
	v_pk_mul_f32 v[32:33], v[20:21], v[244:245] op_sel_hi:[1,0]
	v_rcp_f32_e32 v28, v28
	v_rcp_f32_e32 v29, v29
	v_exp_f32_e32 v32, v32
	v_exp_f32_e32 v33, v33
	v_pk_mul_f32 v[28:29], v[30:31], v[28:29]
	v_add_f32_e32 v30, 1.0, v32
	v_add_f32_e32 v31, 1.0, v33
	v_pk_mul_f32 v[32:33], v[22:23], v[244:245] op_sel_hi:[1,0]
	v_exp_f32_e32 v32, v32
	v_exp_f32_e32 v33, v33
	v_rcp_f32_e32 v30, v30
	v_rcp_f32_e32 v31, v31
	v_pk_add_f32 v[32:33], v[32:33], 1.0 op_sel_hi:[1,0]
	v_rcp_f32_e32 v32, v32
	v_rcp_f32_e32 v33, v33
	v_pk_mul_f32 v[20:21], v[20:21], v[30:31]
	v_pk_mul_f32 v[26:27], v[26:27], v[28:29]
	v_pk_mul_f32 v[20:21], v[16:17], v[20:21]
	v_pk_mul_f32 v[16:17], v[22:23], v[32:33]
	s_nop 0
	v_pk_mul_f32 v[22:23], v[18:19], v[16:17]
	v_mul_f32_e32 v19, 0xbfb8aa3b, v12
	v_cvt_pk_bf16_f32 v18, v20, v21
	v_exp_f32_e32 v20, v19
	v_mul_f32_e32 v19, 0xbfb8aa3b, v13
	v_exp_f32_e32 v21, v19
	v_cvt_pk_bf16_f32 v19, v22, v23
	v_add_co_u32_e32 v22, vcc, s52, v112
	v_cvt_pk_bf16_f32 v16, v24, v25
	v_cvt_pk_bf16_f32 v17, v26, v27
	v_pk_add_f32 v[20:21], v[20:21], 1.0 op_sel_hi:[1,0]
	v_addc_co_u32_e32 v23, vcc, 0, v113, vcc
	v_rcp_f32_e32 v20, v20
	v_rcp_f32_e32 v21, v21
	global_store_dwordx4 v[22:23], v[16:19], off
	v_pk_mul_f32 v[12:13], v[12:13], v[20:21]
	s_nop 0
	v_pk_mul_f32 v[16:17], v[14:15], v[244:245] op_sel_hi:[1,0]
	v_exp_f32_e32 v16, v16
	v_exp_f32_e32 v17, v17
	v_pk_mul_f32 v[8:9], v[8:9], v[12:13]
	v_add_f32_e32 v12, 1.0, v16
	v_add_f32_e32 v13, 1.0, v17
	v_pk_mul_f32 v[16:17], v[4:5], v[244:245] op_sel_hi:[1,0]
	v_rcp_f32_e32 v12, v12
	v_rcp_f32_e32 v13, v13
	v_exp_f32_e32 v16, v16
	v_exp_f32_e32 v17, v17
	v_pk_mul_f32 v[12:13], v[14:15], v[12:13]
	v_add_f32_e32 v14, 1.0, v16
	v_add_f32_e32 v15, 1.0, v17
	v_pk_mul_f32 v[16:17], v[6:7], v[244:245] op_sel_hi:[1,0]
	v_exp_f32_e32 v16, v16
	v_exp_f32_e32 v17, v17
	v_rcp_f32_e32 v14, v14
	v_rcp_f32_e32 v15, v15
	v_pk_add_f32 v[16:17], v[16:17], 1.0 op_sel_hi:[1,0]
	v_rcp_f32_e32 v16, v16
	v_rcp_f32_e32 v17, v17
	v_pk_mul_f32 v[4:5], v[4:5], v[14:15]
	v_pk_mul_f32 v[10:11], v[10:11], v[12:13]
	v_pk_mul_f32 v[4:5], v[0:1], v[4:5]
	v_pk_mul_f32 v[0:1], v[6:7], v[16:17]
	s_nop 0
	v_pk_mul_f32 v[6:7], v[2:3], v[0:1]
	v_cvt_pk_bf16_f32 v2, v4, v5
	v_add_co_u32_e32 v4, vcc, 0xf2000, v112
	v_cvt_pk_bf16_f32 v0, v8, v9
	s_nop 0
	v_addc_co_u32_e32 v5, vcc, 0, v113, vcc
	v_cvt_pk_bf16_f32 v1, v10, v11
	v_cvt_pk_bf16_f32 v3, v6, v7
	s_and_b64 vcc, exec, s[4:5]
	s_mov_b64 s[4:5], -1
	global_store_dwordx4 v[4:5], v[0:3], off
	s_cbranch_vccnz .LBB0_426
	s_andn2_b64 vcc, exec, s[74:75]
	s_cbranch_vccnz .LBB0_425
	s_barrier
	s_branch .LBB0_425

.LBB0_1752:
	v_mul_f32_e32 v167, 0xbfb8aa3b, v124
	v_exp_f32_e32 v168, v167
	v_mul_f32_e32 v167, 0xbfb8aa3b, v125
	v_exp_f32_e32 v169, v167
	v_mov_b32_e32 v166, v144
	v_pk_add_f32 v[168:169], v[168:169], 1.0 op_sel_hi:[1,0]
	v_rcp_f32_e32 v168, v168
	v_rcp_f32_e32 v169, v169
	v_mov_b32_e32 v165, v145
	s_ashr_i32 s43, s42, 31
	v_lshlrev_b32_e32 v170, 3, v165
	v_pk_mul_f32 v[124:125], v[124:125], v[168:169]
	v_mul_f32_e32 v165, 0xbfb8aa3b, v126
	v_mul_f32_e32 v168, 0xbfb8aa3b, v127
	v_exp_f32_e32 v165, v165
	v_exp_f32_e32 v168, v168
	v_pk_mul_f32 v[120:121], v[120:121], v[124:125]
	s_lshl_b64 s[42:43], s[42:43], 8
	v_add_f32_e32 v124, 1.0, v165
	v_add_f32_e32 v125, 1.0, v168
	v_mul_f32_e32 v165, 0xbfb8aa3b, v116
	v_rcp_f32_e32 v124, v124
	v_rcp_f32_e32 v125, v125
	v_exp_f32_e32 v165, v165
	v_mul_f32_e32 v168, 0xbfb8aa3b, v117
	v_exp_f32_e32 v168, v168
	v_pk_mul_f32 v[124:125], v[126:127], v[124:125]
	v_add_f32_e32 v126, 1.0, v165
	v_mul_f32_e32 v165, 0xbfb8aa3b, v118
	v_add_f32_e32 v127, 1.0, v168
	v_exp_f32_e32 v165, v165
	v_mul_f32_e32 v168, 0xbfb8aa3b, v119
	v_exp_f32_e32 v169, v168
	v_rcp_f32_e32 v126, v126
	v_add_f32_e32 v165, 1.0, v165
	v_rcp_f32_e32 v127, v127
	v_rcp_f32_e32 v168, v165
	v_add_f32_e32 v165, 1.0, v169
	v_rcp_f32_e32 v169, v165
	v_pk_mul_f32 v[116:117], v[116:117], v[126:127]
	s_add_u32 s42, s42, s92
	v_ashrrev_i32_e32 v167, 31, v166
	v_pk_mul_f32 v[112:113], v[112:113], v[116:117]
	v_pk_mul_f32 v[116:117], v[118:119], v[168:169]
	s_addc_u32 s43, s43, s97
	v_pk_mul_f32 v[122:123], v[122:123], v[124:125]
	v_pk_mul_f32 v[118:119], v[114:115], v[116:117]
	v_lshl_add_u64 v[124:125], s[42:43], 0, v[166:167]
	v_cvt_pk_bf16_f32 v116, v112, v113
	v_mov_b64_e32 v[112:113], s[64:65]
	v_cvt_pk_bf16_f32 v117, v118, v119
	v_mad_u64_u32 v[112:113], s[42:43], v124, s69, v[112:113]
	v_pk_mul_f32 v[118:119], v[108:109], v[244:245] op_sel_hi:[1,0]
	s_lshl_b32 s42, s78, 7
	v_exp_f32_e32 v118, v118
	v_exp_f32_e32 v119, v119
	v_mad_i32_i24 v113, v125, s69, v113
	s_ashr_i32 s43, s42, 31
	v_lshl_add_u64 v[112:113], s[42:43], 1, v[112:113]
	v_ashrrev_i32_e32 v171, 31, v170
	v_lshl_add_u64 v[112:113], v[112:113], 0, s[16:17]
	v_cvt_pk_bf16_f32 v114, v120, v121
	v_cvt_pk_bf16_f32 v115, v122, v123
	v_pk_add_f32 v[118:119], v[118:119], 1.0 op_sel_hi:[1,0]
	v_lshl_add_u64 v[112:113], v[170:171], 1, v[112:113]
	v_rcp_f32_e32 v118, v118
	v_rcp_f32_e32 v119, v119
	global_store_dwordx4 v[112:113], v[114:117], off
	v_pk_mul_f32 v[108:109], v[108:109], v[118:119]
	s_nop 0
	v_pk_mul_f32 v[114:115], v[110:111], v[244:245] op_sel_hi:[1,0]
	v_exp_f32_e32 v114, v114
	v_exp_f32_e32 v115, v115
	v_pk_mul_f32 v[104:105], v[104:105], v[108:109]
	v_add_f32_e32 v108, 1.0, v114
	v_add_f32_e32 v109, 1.0, v115
	v_pk_mul_f32 v[114:115], v[100:101], v[244:245] op_sel_hi:[1,0]
	v_rcp_f32_e32 v108, v108
	v_rcp_f32_e32 v109, v109
	v_exp_f32_e32 v114, v114
	v_exp_f32_e32 v115, v115
	v_pk_mul_f32 v[108:109], v[110:111], v[108:109]
	v_add_f32_e32 v110, 1.0, v114
	v_add_f32_e32 v111, 1.0, v115
	v_pk_mul_f32 v[114:115], v[102:103], v[244:245] op_sel_hi:[1,0]
	v_exp_f32_e32 v114, v114
	v_exp_f32_e32 v115, v115
	v_rcp_f32_e32 v110, v110
	v_rcp_f32_e32 v111, v111
	v_pk_add_f32 v[114:115], v[114:115], 1.0 op_sel_hi:[1,0]
	v_rcp_f32_e32 v114, v114
	v_rcp_f32_e32 v115, v115
	v_pk_mul_f32 v[100:101], v[100:101], v[110:111]
	v_pk_mul_f32 v[106:107], v[106:107], v[108:109]
	v_pk_mul_f32 v[100:101], v[96:97], v[100:101]
	v_pk_mul_f32 v[96:97], v[102:103], v[114:115]
	s_nop 0
	v_pk_mul_f32 v[102:103], v[98:99], v[96:97]
	v_mul_f32_e32 v99, 0xbfb8aa3b, v92
	v_cvt_pk_bf16_f32 v98, v100, v101
	v_exp_f32_e32 v100, v99
	v_mul_f32_e32 v99, 0xbfb8aa3b, v93
	v_exp_f32_e32 v101, v99
	v_cvt_pk_bf16_f32 v99, v102, v103
	v_add_co_u32_e32 v102, vcc, s50, v112
	v_cvt_pk_bf16_f32 v96, v104, v105
	v_cvt_pk_bf16_f32 v97, v106, v107
	v_pk_add_f32 v[100:101], v[100:101], 1.0 op_sel_hi:[1,0]
	v_addc_co_u32_e32 v103, vcc, 0, v113, vcc
	v_rcp_f32_e32 v100, v100
	v_rcp_f32_e32 v101, v101
	global_store_dwordx4 v[102:103], v[96:99], off
	v_pk_mul_f32 v[92:93], v[92:93], v[100:101]
	s_nop 0
	v_pk_mul_f32 v[96:97], v[94:95], v[244:245] op_sel_hi:[1,0]
	v_exp_f32_e32 v96, v96
	v_exp_f32_e32 v97, v97
	v_pk_mul_f32 v[88:89], v[88:89], v[92:93]
	v_add_f32_e32 v92, 1.0, v96
	v_add_f32_e32 v93, 1.0, v97
	v_pk_mul_f32 v[96:97], v[84:85], v[244:245] op_sel_hi:[1,0]
	v_rcp_f32_e32 v92, v92
	v_rcp_f32_e32 v93, v93
	v_exp_f32_e32 v96, v96
	v_exp_f32_e32 v97, v97
	v_pk_mul_f32 v[92:93], v[94:95], v[92:93]
	v_add_f32_e32 v94, 1.0, v96
	v_add_f32_e32 v95, 1.0, v97
	v_pk_mul_f32 v[96:97], v[86:87], v[244:245] op_sel_hi:[1,0]
	v_exp_f32_e32 v96, v96
	v_exp_f32_e32 v97, v97
	v_rcp_f32_e32 v94, v94
	v_rcp_f32_e32 v95, v95
	v_pk_add_f32 v[96:97], v[96:97], 1.0 op_sel_hi:[1,0]
	v_rcp_f32_e32 v96, v96
	v_rcp_f32_e32 v97, v97
	v_pk_mul_f32 v[84:85], v[84:85], v[94:95]
	v_pk_mul_f32 v[90:91], v[90:91], v[92:93]
	v_pk_mul_f32 v[84:85], v[80:81], v[84:85]
	v_pk_mul_f32 v[80:81], v[86:87], v[96:97]
	s_nop 0
	v_pk_mul_f32 v[86:87], v[82:83], v[80:81]
	v_mul_f32_e32 v83, 0xbfb8aa3b, v76
	v_cvt_pk_bf16_f32 v82, v84, v85
	v_exp_f32_e32 v84, v83
	v_mul_f32_e32 v83, 0xbfb8aa3b, v77
	v_exp_f32_e32 v85, v83
	v_cvt_pk_bf16_f32 v83, v86, v87
	v_add_co_u32_e32 v86, vcc, s70, v112
	v_cvt_pk_bf16_f32 v80, v88, v89
	v_cvt_pk_bf16_f32 v81, v90, v91
	v_pk_add_f32 v[84:85], v[84:85], 1.0 op_sel_hi:[1,0]
	v_addc_co_u32_e32 v87, vcc, 0, v113, vcc
	v_rcp_f32_e32 v84, v84
	v_rcp_f32_e32 v85, v85
	global_store_dwordx4 v[86:87], v[80:83], off
	v_pk_mul_f32 v[76:77], v[76:77], v[84:85]
	s_nop 0
	v_pk_mul_f32 v[80:81], v[78:79], v[244:245] op_sel_hi:[1,0]
	v_exp_f32_e32 v80, v80
	v_exp_f32_e32 v81, v81
	v_pk_mul_f32 v[72:73], v[72:73], v[76:77]
	v_add_f32_e32 v76, 1.0, v80
	v_add_f32_e32 v77, 1.0, v81
	v_pk_mul_f32 v[80:81], v[68:69], v[244:245] op_sel_hi:[1,0]
	v_rcp_f32_e32 v76, v76
	v_rcp_f32_e32 v77, v77
	v_exp_f32_e32 v80, v80
	v_exp_f32_e32 v81, v81
	v_pk_mul_f32 v[76:77], v[78:79], v[76:77]
	v_add_f32_e32 v78, 1.0, v80
	v_add_f32_e32 v79, 1.0, v81
	v_pk_mul_f32 v[80:81], v[70:71], v[244:245] op_sel_hi:[1,0]
	v_exp_f32_e32 v80, v80
	v_exp_f32_e32 v81, v81
	v_rcp_f32_e32 v78, v78
	v_rcp_f32_e32 v79, v79
	v_pk_add_f32 v[80:81], v[80:81], 1.0 op_sel_hi:[1,0]
	v_rcp_f32_e32 v80, v80
	v_rcp_f32_e32 v81, v81
	v_pk_mul_f32 v[68:69], v[68:69], v[78:79]
	v_pk_mul_f32 v[74:75], v[74:75], v[76:77]
	v_pk_mul_f32 v[68:69], v[64:65], v[68:69]
	v_pk_mul_f32 v[64:65], v[70:71], v[80:81]
	s_nop 0
	v_pk_mul_f32 v[70:71], v[66:67], v[64:65]
	v_mul_f32_e32 v67, 0xbfb8aa3b, v60
	v_cvt_pk_bf16_f32 v66, v68, v69
	v_exp_f32_e32 v68, v67
	v_mul_f32_e32 v67, 0xbfb8aa3b, v61
	v_exp_f32_e32 v69, v67
	v_cvt_pk_bf16_f32 v67, v70, v71
	v_add_co_u32_e32 v70, vcc, s71, v112
	v_cvt_pk_bf16_f32 v64, v72, v73
	v_cvt_pk_bf16_f32 v65, v74, v75
	v_pk_add_f32 v[68:69], v[68:69], 1.0 op_sel_hi:[1,0]
	v_addc_co_u32_e32 v71, vcc, 0, v113, vcc
	v_rcp_f32_e32 v68, v68
	v_rcp_f32_e32 v69, v69
	global_store_dwordx4 v[70:71], v[64:67], off
	v_pk_mul_f32 v[60:61], v[60:61], v[68:69]
	s_nop 0
	v_pk_mul_f32 v[64:65], v[62:63], v[244:245] op_sel_hi:[1,0]
	v_exp_f32_e32 v64, v64
	v_exp_f32_e32 v65, v65
	v_pk_mul_f32 v[56:57], v[56:57], v[60:61]
	v_add_f32_e32 v60, 1.0, v64
	v_add_f32_e32 v61, 1.0, v65
	v_pk_mul_f32 v[64:65], v[52:53], v[244:245] op_sel_hi:[1,0]
	v_rcp_f32_e32 v60, v60
	v_rcp_f32_e32 v61, v61
	v_exp_f32_e32 v64, v64
	v_exp_f32_e32 v65, v65
	v_pk_mul_f32 v[60:61], v[62:63], v[60:61]
	v_add_f32_e32 v62, 1.0, v64
	v_add_f32_e32 v63, 1.0, v65
	v_pk_mul_f32 v[64:65], v[54:55], v[244:245] op_sel_hi:[1,0]
	v_exp_f32_e32 v64, v64
	v_exp_f32_e32 v65, v65
	v_rcp_f32_e32 v62, v62
	v_rcp_f32_e32 v63, v63
	v_pk_add_f32 v[64:65], v[64:65], 1.0 op_sel_hi:[1,0]
	v_rcp_f32_e32 v64, v64
	v_rcp_f32_e32 v65, v65
	v_pk_mul_f32 v[52:53], v[52:53], v[62:63]
	v_pk_mul_f32 v[58:59], v[58:59], v[60:61]
	v_pk_mul_f32 v[52:53], v[48:49], v[52:53]
	v_pk_mul_f32 v[48:49], v[54:55], v[64:65]
	s_nop 0
	v_pk_mul_f32 v[54:55], v[50:51], v[48:49]
	v_mul_f32_e32 v51, 0xbfb8aa3b, v44
	v_cvt_pk_bf16_f32 v50, v52, v53
	v_exp_f32_e32 v52, v51
	v_mul_f32_e32 v51, 0xbfb8aa3b, v45
	v_exp_f32_e32 v53, v51
	v_cvt_pk_bf16_f32 v51, v54, v55
	v_add_co_u32_e32 v54, vcc, s72, v112
	v_cvt_pk_bf16_f32 v48, v56, v57
	v_cvt_pk_bf16_f32 v49, v58, v59
	v_pk_add_f32 v[52:53], v[52:53], 1.0 op_sel_hi:[1,0]
	v_addc_co_u32_e32 v55, vcc, 0, v113, vcc
	v_rcp_f32_e32 v52, v52
	v_rcp_f32_e32 v53, v53
	global_store_dwordx4 v[54:55], v[48:51], off
	v_pk_mul_f32 v[44:45], v[44:45], v[52:53]
	s_nop 0
	v_pk_mul_f32 v[48:49], v[46:47], v[244:245] op_sel_hi:[1,0]
	v_exp_f32_e32 v48, v48
	v_exp_f32_e32 v49, v49
	v_pk_mul_f32 v[40:41], v[40:41], v[44:45]
	v_add_f32_e32 v44, 1.0, v48
	v_add_f32_e32 v45, 1.0, v49
	v_pk_mul_f32 v[48:49], v[36:37], v[244:245] op_sel_hi:[1,0]
	v_rcp_f32_e32 v44, v44
	v_rcp_f32_e32 v45, v45
	v_exp_f32_e32 v48, v48
	v_exp_f32_e32 v49, v49
	v_pk_mul_f32 v[44:45], v[46:47], v[44:45]
	v_add_f32_e32 v46, 1.0, v48
	v_add_f32_e32 v47, 1.0, v49
	v_pk_mul_f32 v[48:49], v[38:39], v[244:245] op_sel_hi:[1,0]
	v_exp_f32_e32 v48, v48
	v_exp_f32_e32 v49, v49
	v_rcp_f32_e32 v46, v46
	v_rcp_f32_e32 v47, v47
	v_pk_add_f32 v[48:49], v[48:49], 1.0 op_sel_hi:[1,0]
	v_rcp_f32_e32 v48, v48
	v_rcp_f32_e32 v49, v49
	v_pk_mul_f32 v[36:37], v[36:37], v[46:47]
	v_pk_mul_f32 v[42:43], v[42:43], v[44:45]
	v_pk_mul_f32 v[36:37], v[32:33], v[36:37]
	v_pk_mul_f32 v[32:33], v[38:39], v[48:49]
	s_nop 0
	v_pk_mul_f32 v[38:39], v[34:35], v[32:33]
	v_mul_f32_e32 v35, 0xbfb8aa3b, v28
	v_cvt_pk_bf16_f32 v34, v36, v37
	v_exp_f32_e32 v36, v35
	v_mul_f32_e32 v35, 0xbfb8aa3b, v29
	v_exp_f32_e32 v37, v35
	v_cvt_pk_bf16_f32 v35, v38, v39
	v_add_co_u32_e32 v38, vcc, s73, v112
	v_cvt_pk_bf16_f32 v32, v40, v41
	v_cvt_pk_bf16_f32 v33, v42, v43
	v_pk_add_f32 v[36:37], v[36:37], 1.0 op_sel_hi:[1,0]
	v_addc_co_u32_e32 v39, vcc, 0, v113, vcc
	v_rcp_f32_e32 v36, v36
	v_rcp_f32_e32 v37, v37
	global_store_dwordx4 v[38:39], v[32:35], off
	v_pk_mul_f32 v[28:29], v[28:29], v[36:37]
	s_nop 0
	v_pk_mul_f32 v[32:33], v[30:31], v[244:245] op_sel_hi:[1,0]
	v_exp_f32_e32 v32, v32
	v_exp_f32_e32 v33, v33
	v_pk_mul_f32 v[24:25], v[24:25], v[28:29]
	v_add_f32_e32 v28, 1.0, v32
	v_add_f32_e32 v29, 1.0, v33
	v_pk_mul_f32 v[32:33], v[20:21], v[244:245] op_sel_hi:[1,0]
	v_rcp_f32_e32 v28, v28
	v_rcp_f32_e32 v29, v29
	v_exp_f32_e32 v32, v32
	v_exp_f32_e32 v33, v33
	v_pk_mul_f32 v[28:29], v[30:31], v[28:29]
	v_add_f32_e32 v30, 1.0, v32
	v_add_f32_e32 v31, 1.0, v33
	v_pk_mul_f32 v[32:33], v[22:23], v[244:245] op_sel_hi:[1,0]
	v_exp_f32_e32 v32, v32
	v_exp_f32_e32 v33, v33
	v_rcp_f32_e32 v30, v30
	v_rcp_f32_e32 v31, v31
	v_pk_add_f32 v[32:33], v[32:33], 1.0 op_sel_hi:[1,0]
	v_rcp_f32_e32 v32, v32
	v_rcp_f32_e32 v33, v33
	v_pk_mul_f32 v[20:21], v[20:21], v[30:31]
	v_pk_mul_f32 v[26:27], v[26:27], v[28:29]
	v_pk_mul_f32 v[20:21], v[16:17], v[20:21]
	v_pk_mul_f32 v[16:17], v[22:23], v[32:33]
	s_nop 0
	v_pk_mul_f32 v[22:23], v[18:19], v[16:17]
	v_mul_f32_e32 v19, 0xbfb8aa3b, v12
	v_cvt_pk_bf16_f32 v18, v20, v21
	v_exp_f32_e32 v20, v19
	v_mul_f32_e32 v19, 0xbfb8aa3b, v13
	v_exp_f32_e32 v21, v19
	v_cvt_pk_bf16_f32 v19, v22, v23
	v_add_co_u32_e32 v22, vcc, s74, v112
	v_cvt_pk_bf16_f32 v16, v24, v25
	v_cvt_pk_bf16_f32 v17, v26, v27
	v_pk_add_f32 v[20:21], v[20:21], 1.0 op_sel_hi:[1,0]
	v_addc_co_u32_e32 v23, vcc, 0, v113, vcc
	v_rcp_f32_e32 v20, v20
	v_rcp_f32_e32 v21, v21
	global_store_dwordx4 v[22:23], v[16:19], off
	v_pk_mul_f32 v[12:13], v[12:13], v[20:21]
	s_nop 0
	v_pk_mul_f32 v[16:17], v[14:15], v[244:245] op_sel_hi:[1,0]
	v_exp_f32_e32 v16, v16
	v_exp_f32_e32 v17, v17
	v_pk_mul_f32 v[8:9], v[8:9], v[12:13]
	v_add_f32_e32 v12, 1.0, v16
	v_add_f32_e32 v13, 1.0, v17
	v_pk_mul_f32 v[16:17], v[4:5], v[244:245] op_sel_hi:[1,0]
	v_rcp_f32_e32 v12, v12
	v_rcp_f32_e32 v13, v13
	v_exp_f32_e32 v16, v16
	v_exp_f32_e32 v17, v17
	v_pk_mul_f32 v[12:13], v[14:15], v[12:13]
	v_add_f32_e32 v14, 1.0, v16
	v_add_f32_e32 v15, 1.0, v17
	v_pk_mul_f32 v[16:17], v[6:7], v[244:245] op_sel_hi:[1,0]
	v_exp_f32_e32 v16, v16
	v_exp_f32_e32 v17, v17
	v_rcp_f32_e32 v14, v14
	v_rcp_f32_e32 v15, v15
	v_pk_add_f32 v[16:17], v[16:17], 1.0 op_sel_hi:[1,0]
	v_rcp_f32_e32 v16, v16
	v_rcp_f32_e32 v17, v17
	v_pk_mul_f32 v[4:5], v[4:5], v[14:15]
	v_pk_mul_f32 v[10:11], v[10:11], v[12:13]
	v_pk_mul_f32 v[4:5], v[0:1], v[4:5]
	v_pk_mul_f32 v[0:1], v[6:7], v[16:17]
	s_nop 0
	v_pk_mul_f32 v[6:7], v[2:3], v[0:1]
	v_cvt_pk_bf16_f32 v2, v4, v5
	v_add_co_u32_e32 v4, vcc, 0xf2000, v112
	v_cvt_pk_bf16_f32 v0, v8, v9
	s_nop 0
	v_addc_co_u32_e32 v5, vcc, 0, v113, vcc
	v_cvt_pk_bf16_f32 v1, v10, v11
	v_cvt_pk_bf16_f32 v3, v6, v7
	s_and_b64 vcc, exec, s[6:7]
	s_mov_b64 s[6:7], -1
	global_store_dwordx4 v[4:5], v[0:3], off
	s_cbranch_vccnz .LBB0_1740
	s_andn2_b64 vcc, exec, s[18:19]
	s_cbranch_vccnz .LBB0_1739
	s_barrier
	s_branch .LBB0_1739
